# attention sample items: mask rows staged in LDS too (same change as v105 for the prompt items)
# speedup vs baseline: 1.0028x; 1.0028x over previous
; DI float bf2f(bfr b) { return __uint_as_float(((unsigned)b) << 16); }
; DI void attn_block(const Params& p, int isP, int sq, int c, int h) {
;     ...
;     T0 = 0; nqt = 4; nadm = S_S; rowbase = ROWS_P + sq * 64;
;     kb = (const bfr*)(p.ws + W_KBS) + (long)sq * S_S * 512;
;     vt = (const bfr*)(p.ws + W_VTS) + (long)sq * 512 * S_S;
;     vld = S_S;
;   }
;   const int nsteps = (nadm + 31) >> 5;
;   const int qrow0 = rowbase + T0;
;   const bfr* qb = (const bfr*)(p.ws + W_QB);
;   const unsigned* maskg = (const unsigned*)(p.ws + W_MASK);
;   bf16x8 qf[4][2];
; #pragma unroll
;   for (int qt = 0; qt < 4; ++qt)
; #pragma unroll
;     for (int ks = 0; ks < 2; ++ks) {
;       int r = qrow0 + (qt < nqt ? qt * 16 : 0) + fr;
;       qf[qt][ks] = *(const bf16x8*)(qb + (long)r * 512 + h * 64 + ks * 32 + fq * 8);
;     }
;   f32x4 o[4][4];
; #pragma unroll
;   for (int qt = 0; qt < 4; ++qt)
; #pragma unroll
;     for (int dt = 0; dt < 4; ++dt) o[qt][dt] = f32x4{0.f, 0.f, 0.f, 0.f};
;   const float sc2 = 0.125f * 1.4426950408889634f;
;   const float kmax2 = ((const float*)(p.ws + W_KMAX))[(isP ? sq : NB_P + sq) * 8 + h];
;   float mref[4], lsum[4] = {0.f, 0.f, 0.f, 0.f};
;   const unsigned* mrow[4];
; #pragma unroll
;   for (int qt = 0; qt < 4; ++qt) {
;     float ss = 0.f;
; #pragma unroll
;     for (int ks = 0; ks < 2; ++ks)
; #pragma unroll
;       for (int i = 0; i < 8; ++i) { float a = bf2f((bfr)qf[qt][ks][i]); ss += a * a; }
;     ss += __shfl_xor(ss, 16);
;     ss += __shfl_xor(ss, 32);
;     mref[qt] = sqrtf(ss * kmax2) * sc2;
.LBB0_4850:
	s_and_b64 vcc, exec, s[0:1]
	s_cbranch_vccz .LBB0_4858
	s_add_i32 s0, s18, 0xfffff800
	s_lshr_b32 s22, s0, 3
	v_mov_b32_e32 v99, v158
	s_and_b32 s1, s18, 7
	s_lshl_b32 s7, s22, 6
	v_readfirstlane_b32 s19, v99
	s_ashr_i32 s6, s19, 6
	s_addk_i32 s7, 0x4040
	s_lshl_b32 s20, s1, 6
	s_lshl_b32 s21, s1, 7
	v_and_b32_e32 v122, 15, v99
	s_add_u32 s8, s12, s21
	v_or_b32_e32 v128, s7, v122
	s_addc_u32 s9, s13, 0
	v_and_b32_e32 v114, 48, v99
	v_mov_b32_e32 v115, v129
	v_lshl_add_u64 v[0:1], s[8:9], 0, v[114:115]
	v_lshlrev_b64 v[2:3], 10, v[128:129]
	v_lshl_add_u64 v[2:3], v[0:1], 0, v[2:3]
	global_load_dwordx4 v[8:11], v[2:3], off
	global_load_dwordx4 v[16:19], v[2:3], off offset:64
	v_or_b32_e32 v108, 16, v128
	v_mov_b32_e32 v109, v129
	v_lshlrev_b64 v[2:3], 10, v[108:109]
	v_lshl_add_u64 v[2:3], v[0:1], 0, v[2:3]
	global_load_dwordx4 v[28:31], v[2:3], off
	global_load_dwordx4 v[32:35], v[2:3], off offset:64
	v_and_b32_e32 v3, 64, v164
	v_xor_b32_e32 v2, 16, v164
	v_add_u32_e32 v5, 64, v3
	v_mov_b32_e32 v97, v129
	s_waitcnt vmcnt(4)
	v_xor_b32_e32 v4, 32, v164
	v_cmp_lt_i32_e32 vcc, v2, v5
	v_or_b32_e32 v96, 32, v128
	v_mov_b32_e32 v113, v129
	v_cndmask_b32_e32 v7, v164, v2, vcc
	v_lshlrev_b64 v[2:3], 10, v[96:97]
	v_cmp_lt_i32_e32 vcc, v4, v5
	v_lshl_add_u64 v[2:3], v[0:1], 0, v[2:3]
	v_or_b32_e32 v112, 48, v128
	v_cndmask_b32_e32 v4, v164, v4, vcc
	global_load_dwordx4 v[48:51], v[2:3], off
	v_lshlrev_b32_e32 v116, 2, v4
	v_lshlrev_b64 v[4:5], 10, v[112:113]
	v_lshl_add_u64 v[0:1], v[0:1], 0, v[4:5]
	global_load_dwordx4 v[52:55], v[2:3], off offset:64
	global_load_dwordx4 v[56:59], v[0:1], off
	global_load_dwordx4 v[60:63], v[0:1], off offset:64
	v_bfe_u32 v6, v99, 4, 2
	v_lshlrev_b32_e32 v98, 3, v6
	v_lshlrev_b32_e32 v117, 2, v7
	v_mov_b32_e32 v101, 0
	v_readfirstlane_b32 s100, v128
	v_readlane_b32 s98, v251, 22
	v_readlane_b32 s99, v251, 23
	s_mul_i32 s101, s100, 0x210
	s_add_u32 s98, s98, s101
	s_addc_u32 s99, s99, 0
	v_and_b32_e32 v206, 63, v99
	v_lshlrev_b32_e32 v206, 4, v206
	v_mov_b32_e32 v207, 0
	v_lshl_add_u64 v[206:207], s[98:99], 0, v[206:207]
	s_lshl_b32 s100, s6, 10
	v_mov_b32_e32 v209, 0
.Lmf2_loop:
	v_mov_b32_e32 v208, s100
	s_add_i32 s101, s100, 0x80
	s_mov_b32 m0, s101
	v_lshl_add_u64 v[210:211], v[206:207], 0, v[208:209]
	global_load_lds_dwordx4 v[210:211], off
	s_addk_i32 s100, 0x1000
	s_cmpk_lt_u32 s100, 0x8400
	s_cbranch_scc1 .Lmf2_loop
	s_cmpk_gt_i32 s6, 0x41
	v_mov_b32_e32 v100, v101
	v_mov_b32_e32 v105, v101
	v_mov_b32_e32 v104, v101
	v_mov_b32_e32 v47, v101
	v_mov_b32_e32 v46, v101
	v_mov_b32_e32 v45, v101
	v_mov_b32_e32 v71, v101
	v_mov_b32_e32 v70, v101
	v_mov_b32_e32 v69, v101
	v_mov_b32_e32 v68, v101
	v_mov_b32_e32 v75, v101
	v_mov_b32_e32 v74, v101
	v_mov_b32_e32 v73, v101
	v_mov_b32_e32 v72, v101
	v_mov_b32_e32 v79, v101
	v_mov_b32_e32 v78, v101
	v_mov_b32_e32 v77, v101
	v_mov_b32_e32 v76, v101
	v_mov_b32_e32 v83, v101
	v_mov_b32_e32 v82, v101
	v_mov_b32_e32 v81, v101
	v_mov_b32_e32 v80, v101
	v_mov_b32_e32 v87, v101
	v_mov_b32_e32 v86, v101
	v_mov_b32_e32 v85, v101
	v_mov_b32_e32 v84, v101
	v_mov_b32_e32 v91, v101
	v_mov_b32_e32 v90, v101
	v_mov_b32_e32 v89, v101
	v_mov_b32_e32 v88, v101
	v_mov_b32_e32 v95, v101
	v_mov_b32_e32 v94, v101
	v_mov_b32_e32 v93, v101
	v_mov_b32_e32 v92, v101
	v_mov_b32_e32 v67, v101
	v_mov_b32_e32 v66, v101
	v_mov_b32_e32 v65, v101
	v_mov_b32_e32 v64, v101
	s_waitcnt vmcnt(7)
	v_and_b32_e32 v1, 0xffff0000, v8
	v_lshlrev_b32_e32 v0, 16, v8
	v_mul_f32_e32 v1, v1, v1
	v_lshlrev_b32_e32 v2, 16, v9
	v_fmac_f32_e32 v1, v0, v0
	v_and_b32_e32 v3, 0xffff0000, v9
	v_fmac_f32_e32 v1, v2, v2
	v_lshlrev_b32_e32 v4, 16, v10
	v_fmac_f32_e32 v1, v3, v3
	v_and_b32_e32 v5, 0xffff0000, v10
	v_fmac_f32_e32 v1, v4, v4
	v_lshlrev_b32_e32 v6, 16, v11
	v_fmac_f32_e32 v1, v5, v5
	v_and_b32_e32 v7, 0xffff0000, v11
	v_fmac_f32_e32 v1, v6, v6
	s_waitcnt vmcnt(6)
	v_lshlrev_b32_e32 v12, 16, v16
	v_fmac_f32_e32 v1, v7, v7
	v_and_b32_e32 v13, 0xffff0000, v16
	v_fmac_f32_e32 v1, v12, v12
	v_lshlrev_b32_e32 v14, 16, v17
	v_fmac_f32_e32 v1, v13, v13
	v_and_b32_e32 v15, 0xffff0000, v17
	v_fmac_f32_e32 v1, v14, v14
	v_lshlrev_b32_e32 v20, 16, v18
	v_fmac_f32_e32 v1, v15, v15
	v_and_b32_e32 v21, 0xffff0000, v18
	v_fmac_f32_e32 v1, v20, v20
	v_lshlrev_b32_e32 v22, 16, v19
	v_fmac_f32_e32 v1, v21, v21
	v_and_b32_e32 v23, 0xffff0000, v19
	v_fmac_f32_e32 v1, v22, v22
	v_fmac_f32_e32 v1, v23, v23
	ds_bpermute_b32 v0, v117, v1
	s_waitcnt vmcnt(5)
	v_and_b32_e32 v25, 0xffff0000, v28
	s_waitcnt vmcnt(3)
	v_and_b32_e32 v2, 0xffff0000, v48
	s_waitcnt vmcnt(1)
	v_and_b32_e32 v4, 0xffff0000, v56
	v_lshlrev_b32_e32 v24, 16, v28
	v_mul_f32_e32 v25, v25, v25
	s_waitcnt lgkmcnt(0)
	v_add_f32_e32 v107, v1, v0
	v_lshlrev_b32_e32 v1, 16, v48
	v_mul_f32_e32 v2, v2, v2
	v_lshlrev_b32_e32 v3, 16, v56
	v_mul_f32_e32 v4, v4, v4
	v_lshlrev_b32_e32 v26, 16, v29
	v_fmac_f32_e32 v25, v24, v24
	v_fmac_f32_e32 v2, v1, v1
	v_lshlrev_b32_e32 v1, 16, v49
	v_fmac_f32_e32 v4, v3, v3
	v_lshlrev_b32_e32 v3, 16, v57
	v_and_b32_e32 v27, 0xffff0000, v29
	v_fmac_f32_e32 v25, v26, v26
	v_fmac_f32_e32 v2, v1, v1
	v_and_b32_e32 v1, 0xffff0000, v49
	v_fmac_f32_e32 v4, v3, v3
	v_and_b32_e32 v3, 0xffff0000, v57
	v_lshlrev_b32_e32 v36, 16, v30
	v_fmac_f32_e32 v25, v27, v27
	v_fmac_f32_e32 v2, v1, v1
	v_lshlrev_b32_e32 v1, 16, v50
	v_fmac_f32_e32 v4, v3, v3
	v_lshlrev_b32_e32 v3, 16, v58
	v_and_b32_e32 v37, 0xffff0000, v30
	v_fmac_f32_e32 v25, v36, v36
	v_fmac_f32_e32 v2, v1, v1
	v_and_b32_e32 v1, 0xffff0000, v50
	v_fmac_f32_e32 v4, v3, v3
	v_and_b32_e32 v3, 0xffff0000, v58
	v_lshlrev_b32_e32 v38, 16, v31
	v_fmac_f32_e32 v25, v37, v37
	v_fmac_f32_e32 v2, v1, v1
	v_lshlrev_b32_e32 v1, 16, v51
	v_fmac_f32_e32 v4, v3, v3
	v_lshlrev_b32_e32 v3, 16, v59
	v_and_b32_e32 v39, 0xffff0000, v31
	v_fmac_f32_e32 v25, v38, v38
	v_fmac_f32_e32 v2, v1, v1
	v_and_b32_e32 v1, 0xffff0000, v51
	v_fmac_f32_e32 v4, v3, v3
	v_and_b32_e32 v3, 0xffff0000, v59
	v_lshlrev_b32_e32 v40, 16, v32
	v_fmac_f32_e32 v25, v39, v39
	v_fmac_f32_e32 v2, v1, v1
	v_lshlrev_b32_e32 v1, 16, v52
	v_fmac_f32_e32 v4, v3, v3
	s_waitcnt vmcnt(0)
	s_barrier
; DI float bf2f(bfr b) { return __uint_as_float(((unsigned)b) << 16); }
; DI void attn_block(const Params& p, int isP, int sq, int c, int h) {
;     ...
;   f32x4 o[4][4];
; #pragma unroll
;   for (int qt = 0; qt < 4; ++qt)
; #pragma unroll
;     for (int dt = 0; dt < 4; ++dt) o[qt][dt] = f32x4{0.f, 0.f, 0.f, 0.f};
;   const float sc2 = 0.125f * 1.4426950408889634f;
;   const float kmax2 = ((const float*)(p.ws + W_KMAX))[(isP ? sq : NB_P + sq) * 8 + h];
;   float mref[4], lsum[4] = {0.f, 0.f, 0.f, 0.f};
;   const unsigned* mrow[4];
; #pragma unroll
;   for (int qt = 0; qt < 4; ++qt) {
;     float ss = 0.f;
; #pragma unroll
;     for (int ks = 0; ks < 2; ++ks)
; #pragma unroll
;       for (int i = 0; i < 8; ++i) { float a = bf2f((bfr)qf[qt][ks][i]); ss += a * a; }
;     ss += __shfl_xor(ss, 16);
;     ss += __shfl_xor(ss, 32);
;     mref[qt] = sqrtf(ss * kmax2) * sc2;
	v_lshlrev_b32_e32 v3, 16, v60
	v_and_b32_e32 v41, 0xffff0000, v32
	v_fmac_f32_e32 v25, v40, v40
	v_fmac_f32_e32 v2, v1, v1
	v_and_b32_e32 v1, 0xffff0000, v52
	v_fmac_f32_e32 v4, v3, v3
	v_and_b32_e32 v3, 0xffff0000, v60
	v_lshlrev_b32_e32 v42, 16, v33
	v_fmac_f32_e32 v25, v41, v41
	v_fmac_f32_e32 v2, v1, v1
	v_lshlrev_b32_e32 v1, 16, v53
	v_fmac_f32_e32 v4, v3, v3
	v_lshlrev_b32_e32 v3, 16, v61
	v_and_b32_e32 v43, 0xffff0000, v33
	v_fmac_f32_e32 v25, v42, v42
	v_fmac_f32_e32 v2, v1, v1
	v_and_b32_e32 v1, 0xffff0000, v53
	v_fmac_f32_e32 v4, v3, v3
	v_and_b32_e32 v3, 0xffff0000, v61
	v_lshlrev_b32_e32 v44, 16, v34
	v_fmac_f32_e32 v25, v43, v43
	v_fmac_f32_e32 v2, v1, v1
	v_lshlrev_b32_e32 v1, 16, v54
	v_fmac_f32_e32 v4, v3, v3
	v_lshlrev_b32_e32 v3, 16, v62
	v_fmac_f32_e32 v25, v44, v44
	v_and_b32_e32 v0, 0xffff0000, v34
	v_fmac_f32_e32 v2, v1, v1
	v_and_b32_e32 v1, 0xffff0000, v54
	v_fmac_f32_e32 v4, v3, v3
	v_and_b32_e32 v3, 0xffff0000, v62
	v_fmac_f32_e32 v25, v0, v0
	v_lshlrev_b32_e32 v0, 16, v35
	v_fmac_f32_e32 v2, v1, v1
	v_lshlrev_b32_e32 v1, 16, v55
	v_fmac_f32_e32 v4, v3, v3
	v_lshlrev_b32_e32 v3, 16, v63
	v_fmac_f32_e32 v25, v0, v0
	v_and_b32_e32 v0, 0xffff0000, v35
	v_fmac_f32_e32 v2, v1, v1
	v_and_b32_e32 v1, 0xffff0000, v55
	v_fmac_f32_e32 v4, v3, v3
	v_and_b32_e32 v3, 0xffff0000, v63
	v_fmac_f32_e32 v25, v0, v0
	v_fmac_f32_e32 v2, v1, v1
	v_fmac_f32_e32 v4, v3, v3
	ds_bpermute_b32 v0, v117, v25
	ds_bpermute_b32 v1, v117, v2
	ds_bpermute_b32 v3, v117, v4
	ds_bpermute_b32 v109, v116, v107
	v_mov_b32_e32 v7, v101
	s_waitcnt lgkmcnt(3)
	v_add_f32_e32 v110, v25, v0
	s_waitcnt lgkmcnt(2)
	v_add_f32_e32 v103, v2, v1
	s_waitcnt lgkmcnt(1)
	v_add_f32_e32 v97, v4, v3
	ds_bpermute_b32 v111, v116, v110
	ds_bpermute_b32 v106, v116, v103
	ds_bpermute_b32 v102, v116, v97
	v_mov_b32_e32 v3, v101
	v_mov_b32_e32 v2, v101
	v_mov_b32_e32 v1, v101
	v_mov_b32_e32 v0, v101
	v_mov_b32_e32 v6, v101
	v_mov_b32_e32 v5, v101
	v_mov_b32_e32 v4, v101
	v_mov_b32_e32 v15, v101
	v_mov_b32_e32 v14, v101
	v_mov_b32_e32 v13, v101
	v_mov_b32_e32 v12, v101
	v_mov_b32_e32 v23, v101
	v_mov_b32_e32 v22, v101
	v_mov_b32_e32 v21, v101
	v_mov_b32_e32 v20, v101
	v_mov_b32_e32 v27, v101
	v_mov_b32_e32 v26, v101
	v_mov_b32_e32 v25, v101
	v_mov_b32_e32 v24, v101
	v_mov_b32_e32 v39, v101
	v_mov_b32_e32 v38, v101
	v_mov_b32_e32 v37, v101
	v_mov_b32_e32 v36, v101
	v_mov_b32_e32 v43, v101
	v_mov_b32_e32 v42, v101
	v_mov_b32_e32 v41, v101
	v_mov_b32_e32 v40, v101
	v_mov_b32_e32 v44, v101
	s_cbranch_scc1 .LBB0_4854
	s_mul_i32 s22, s22, 0x210000
	s_add_u32 s8, s16, s22
	s_addc_u32 s9, s17, 0
	s_and_b32 s0, s0, -8
	s_or_b32 s0, s0, s1
	s_add_i32 s90, s0, 32
	s_lshl_b64 s[0:1], s[90:91], 2
	s_add_u32 s0, s2, s0
	s_addc_u32 s1, s3, s1
	global_load_dword v0, v129, s[0:1]
	s_waitcnt lgkmcnt(3)
	v_add_f32_e32 v1, v107, v109
	s_mov_b32 s7, 0xf800000
	v_readlane_b32 s24, v249, 0
	v_readlane_b32 s25, v249, 1
	v_mov_b32_e32 v64, 0
	v_mov_b32_e32 v65, v64
	v_mov_b32_e32 v66, v64
	v_mov_b32_e32 v67, v64
	v_mov_b32_e32 v92, v64
	v_mov_b32_e32 v93, v64
	v_mov_b32_e32 v94, v64
	v_mov_b32_e32 v95, v64
	v_mov_b32_e32 v88, v64
	v_mov_b32_e32 v89, v64
	v_mov_b32_e32 v90, v64
	v_mov_b32_e32 v91, v64
	v_mov_b32_e32 v84, v64
	v_mov_b32_e32 v85, v64
	v_mov_b32_e32 v86, v64
	v_mov_b32_e32 v87, v64
	v_mov_b32_e32 v80, v64
	v_mov_b32_e32 v81, v64
	v_mov_b32_e32 v82, v64
	v_mov_b32_e32 v83, v64
	v_mov_b32_e32 v76, v64
	v_mov_b32_e32 v77, v64
	v_mov_b32_e32 v78, v64
	v_mov_b32_e32 v79, v64
	v_mov_b32_e32 v72, v64
	v_mov_b32_e32 v73, v64
	v_mov_b32_e32 v74, v64
	v_mov_b32_e32 v75, v64
	v_mov_b32_e32 v68, v64
	v_mov_b32_e32 v69, v64
	v_mov_b32_e32 v70, v64
	v_mov_b32_e32 v71, v64
	v_mov_b32_e32 v44, v64
	v_mov_b32_e32 v45, v64
	v_mov_b32_e32 v46, v64
	v_mov_b32_e32 v47, v64
	v_mov_b32_e32 v40, v64
	v_mov_b32_e32 v41, v64
	v_mov_b32_e32 v42, v64
	v_mov_b32_e32 v43, v64
	v_mov_b32_e32 v36, v64
	v_mov_b32_e32 v37, v64
	v_mov_b32_e32 v38, v64
	v_mov_b32_e32 v39, v64
	v_mov_b32_e32 v24, v64
	v_mov_b32_e32 v25, v64
	v_mov_b32_e32 v26, v64
	v_mov_b32_e32 v27, v64
	v_mov_b32_e32 v20, v64
	v_mov_b32_e32 v21, v64
	v_mov_b32_e32 v22, v64
	v_mov_b32_e32 v23, v64
	v_mov_b32_e32 v12, v64
	v_mov_b32_e32 v13, v64
	v_mov_b32_e32 v14, v64
	v_mov_b32_e32 v15, v64
	v_mov_b32_e32 v5, v64
	v_mov_b32_e32 v6, v64
	v_mov_b32_e32 v7, v64
	v_mov_b32_e32 v104, v64
	v_mov_b32_e32 v105, v64
	v_mov_b32_e32 v100, v64
	v_mov_b32_e32 v101, v64
	v_readlane_b32 s26, v249, 2
	v_readlane_b32 s27, v249, 3
	s_waitcnt vmcnt(0)
	v_mul_f32_e32 v1, v0, v1
	v_cmp_gt_f32_e32 vcc, s7, v1
	v_mul_f32_e32 v2, 0x4f800000, v1
	s_nop 0
	v_cndmask_b32_e32 v1, v1, v2, vcc
	v_sqrt_f32_e32 v2, v1
	s_nop 0
	v_add_u32_e32 v3, -1, v2
	v_fma_f32 v4, -v3, v2, v1
	v_cmp_ge_f32_e64 s[0:1], 0, v4
	v_add_u32_e32 v4, 1, v2
	s_nop 0
	v_cndmask_b32_e64 v3, v2, v3, s[0:1]
	v_fma_f32 v2, -v4, v2, v1
	v_cmp_lt_f32_e64 s[0:1], 0, v2
	s_nop 1
	v_cndmask_b32_e64 v2, v3, v4, s[0:1]
	v_mul_f32_e32 v3, 0x37800000, v2
	v_cndmask_b32_e32 v2, v2, v3, vcc
	v_cmp_class_f32_e32 vcc, v1, v161
	s_nop 1
	v_cndmask_b32_e32 v1, v2, v1, vcc
	v_mul_f32_e32 v118, 0x3e38aa3b, v1
	s_waitcnt lgkmcnt(2)
	v_add_f32_e32 v1, v110, v111
	v_mul_f32_e32 v1, v0, v1
	v_cmp_gt_f32_e32 vcc, s7, v1
	v_mul_f32_e32 v2, 0x4f800000, v1
	s_nop 0
	v_cndmask_b32_e32 v1, v1, v2, vcc
	v_sqrt_f32_e32 v2, v1
	s_nop 0
	v_add_u32_e32 v3, -1, v2
	v_fma_f32 v4, -v3, v2, v1
	v_cmp_ge_f32_e64 s[0:1], 0, v4
	v_add_u32_e32 v4, 1, v2
	s_nop 0
	v_cndmask_b32_e64 v3, v2, v3, s[0:1]
	v_fma_f32 v2, -v4, v2, v1
	v_cmp_lt_f32_e64 s[0:1], 0, v2
	s_nop 1
	v_cndmask_b32_e64 v2, v3, v4, s[0:1]
	v_mul_f32_e32 v3, 0x37800000, v2
	v_cndmask_b32_e32 v2, v2, v3, vcc
	v_cmp_class_f32_e32 vcc, v1, v161
	s_nop 1
	v_cndmask_b32_e32 v1, v2, v1, vcc
	v_mul_f32_e32 v119, 0x3e38aa3b, v1
	s_waitcnt lgkmcnt(1)
; DI void attn_block(const Params& p, int isP, int sq, int c, int h) {
;     ...
;     mref[qt] = sqrtf(ss * kmax2) * sc2;
;     mrow[qt] = maskg + (long)(qrow0 + (qt < nqt ? qt * 16 : 0) + fr) * MW;
;   }
;   const int kofs = (fr >> 2) * 8 + (fr & 3);
;   const bfr* kptr = kb + (long)kofs * 512 + h * 64 + fq * 8;
;   const bfr* vptr = vt + (long)(h * 64 + fr) * vld + fq * 8;
;   if (wid < nsteps) {
;     int s = wid;
;     const bfr* pa0 = kptr + (long)s * 32 * 512;
;     bf16x8 ka0 = *(const bf16x8*)pa0, ka1 = *(const bf16x8*)(pa0 + 32);
;     bf16x8 kb0 = *(const bf16x8*)(pa0 + 4 * 512), kb1 = *(const bf16x8*)(pa0 + 4 * 512 + 32);
;     bf16x8 vf[4];
; #pragma unroll
;     for (int dt = 0; dt < 4; ++dt) vf[dt] = *(const bf16x8*)(vptr + (long)dt * 16 * vld + s * 32);
;     unsigned mw[4];
; #pragma unroll
;     for (int qt = 0; qt < 4; ++qt) mw[qt] = mrow[qt][s];
;     for (; s < nsteps; s += 4) {
;       const int sn = (s + 4 < nsteps) ? s + 4 : s;
;       const bfr* pa = kptr + (long)sn * 32 * 512;
;       const bf16x8 nka0 = *(const bf16x8*)pa, nka1 = *(const bf16x8*)(pa + 32);
;       const bf16x8 nkb0 = *(const bf16x8*)(pa + 4 * 512), nkb1 = *(const bf16x8*)(pa + 4 * 512 + 32);
;       bf16x8 nvf[4];
; #pragma unroll
;       for (int dt = 0; dt < 4; ++dt) nvf[dt] = *(const bf16x8*)(vptr + (long)dt * 16 * vld + sn * 32);
;       unsigned nmw[4];
; #pragma unroll
;       for (int qt = 0; qt < 4; ++qt) nmw[qt] = mrow[qt][sn];
	v_add_f32_e32 v1, v103, v106
	v_mul_f32_e32 v1, v0, v1
	v_cmp_gt_f32_e32 vcc, s7, v1
	v_mul_f32_e32 v2, 0x4f800000, v1
	s_nop 0
	v_cndmask_b32_e32 v1, v1, v2, vcc
	v_sqrt_f32_e32 v2, v1
	s_nop 0
	v_add_u32_e32 v3, -1, v2
	v_fma_f32 v4, -v3, v2, v1
	v_cmp_ge_f32_e64 s[0:1], 0, v4
	v_add_u32_e32 v4, 1, v2
	s_nop 0
	v_cndmask_b32_e64 v3, v2, v3, s[0:1]
	v_fma_f32 v2, -v4, v2, v1
	v_cmp_lt_f32_e64 s[0:1], 0, v2
	s_nop 1
	v_cndmask_b32_e64 v2, v3, v4, s[0:1]
	v_mul_f32_e32 v3, 0x37800000, v2
	v_cndmask_b32_e32 v2, v2, v3, vcc
	v_cmp_class_f32_e32 vcc, v1, v161
	v_and_b32_e32 v4, 3, v99
	s_nop 0
	v_cndmask_b32_e32 v1, v2, v1, vcc
	v_mul_f32_e32 v120, 0x3e38aa3b, v1
	s_waitcnt lgkmcnt(0)
	v_add_f32_e32 v1, v97, v102
	v_mul_f32_e32 v0, v0, v1
	v_cmp_gt_f32_e32 vcc, s7, v0
	v_mul_f32_e32 v1, 0x4f800000, v0
	s_ashr_i32 s7, s6, 31
	v_cndmask_b32_e32 v0, v0, v1, vcc
	v_sqrt_f32_e32 v1, v0
	v_mov_b32_e32 v97, v98
	v_add_u32_e32 v2, -1, v1
	v_fma_f32 v3, -v2, v1, v0
	v_cmp_ge_f32_e64 s[0:1], 0, v3
	v_add_u32_e32 v3, 1, v1
	s_nop 0
	v_cndmask_b32_e64 v2, v1, v2, s[0:1]
	v_fma_f32 v1, -v3, v1, v0
	v_cmp_lt_f32_e64 s[0:1], 0, v1
	s_nop 1
	v_cndmask_b32_e64 v1, v2, v3, s[0:1]
	v_mul_f32_e32 v2, 0x37800000, v1
	v_cndmask_b32_e32 v1, v1, v2, vcc
	v_cmp_class_f32_e32 vcc, v0, v161
	s_lshl_b64 s[0:1], s[6:7], 2
	v_lshlrev_b32_e32 v2, 1, v98
	v_cndmask_b32_e32 v0, v1, v0, vcc
	v_mul_f32_e32 v121, 0x3e38aa3b, v0
	v_or_b32_e32 v0, s20, v122
	v_mul_u32_u24_e32 v0, 0x840, v0
	v_lshlrev_b32_e32 v0, 1, v0
	v_mov_b32_e32 v1, v129
	v_lshl_add_u64 v[0:1], s[8:9], 0, v[0:1]
	s_add_i32 s8, s6, -4
	v_readlane_b32 s9, v251, 22
	s_add_u32 s0, s9, s0
	v_readlane_b32 s9, v251, 23
	v_mov_b32_e32 v3, v129
	s_addc_u32 s1, s9, s1
	v_lshl_add_u64 v[102:103], v[0:1], 0, v[2:3]
	v_mov_b64_e32 v[0:1], s[0:1]
	v_mad_u64_u32 v[106:107], s[0:1], v128, s86, v[0:1]
	v_mad_u64_u32 v[108:109], s[0:1], v108, s86, v[0:1]
	v_mad_u64_u32 v[110:111], s[0:1], v96, s86, v[0:1]
	v_mad_u64_u32 v[112:113], s[0:1], v112, s86, v[0:1]
	s_lshl_b64 s[0:1], s[6:7], 15
	v_lshlrev_b32_e32 v0, 11, v122
	v_lshlrev_b32_e32 v1, 10, v4
	s_or_b32 s0, s0, s21
	v_and_or_b32 v0, v0, s28, v1
	v_or3_b32 v0, s0, v114, v0
	s_add_u32 s0, s24, s22
	v_mov_b32_e32 v1, s1
	s_addc_u32 s1, s25, 0
	v_lshl_add_u64 v[114:115], s[0:1], 0, v[0:1]
	s_lshl_b32 s0, s6, 5
	v_mov_b32_e32 v4, v64
	v_mov_b32_e32 v0, v64
	v_mov_b32_e32 v1, v64
	v_mov_b32_e32 v2, v64
	v_mov_b32_e32 v3, v64
	s_mov_b64 s[22:23], 0x20000
	v_mul_u32_u24_e32 v208, 0x210, v122
	v_lshl_add_u32 v208, s6, 2, v208
	v_add_u32_e32 v208, 0x80, v208
.LBB0_4853:
	s_ashr_i32 s1, s0, 31
	v_lshl_add_u64 v[126:127], s[0:1], 1, v[102:103]
	v_lshl_add_u64 v[136:137], v[114:115], 0, s[36:37]
	s_mov_b32 s1, 0x187a1000
	v_add_co_u32_e32 v132, vcc, s1, v136
	s_mov_b32 s1, 0x187a0000
	s_nop 0
	v_addc_co_u32_e32 v133, vcc, 0, v137, vcc
	v_add_co_u32_e32 v140, vcc, s1, v136
	global_load_dwordx4 v[122:125], v[132:133], off offset:3136
	s_nop 0
	global_load_dwordx4 v[132:135], v[132:133], off offset:3072
	v_addc_co_u32_e32 v141, vcc, 0, v137, vcc
	global_load_dwordx4 v[136:139], v[140:141], off offset:3136
	s_nop 0
	global_load_dwordx4 v[140:143], v[140:141], off offset:3072
	ds_read_b32 v156, v208
	ds_read_b32 v157, v208 offset:8448
	s_mov_b32 s1, 0x10000
	v_add_co_u32_e32 v148, vcc, s1, v126
	s_mov_b32 s1, 0x21000
	s_nop 0
	v_addc_co_u32_e32 v149, vcc, 0, v127, vcc
	v_add_co_u32_e32 v152, vcc, s1, v126
	ds_read_b32 v159, v208 offset:16896
	v_addc_co_u32_e32 v153, vcc, 0, v127, vcc
	s_mov_b32 s1, 0x31000
	ds_read_b32 v202, v208 offset:25344
	s_nop 0
	global_load_dwordx4 v[144:147], v[126:127], off
	v_add_co_u32_e32 v126, vcc, s1, v126
	global_load_dwordx4 v[148:151], v[148:149], off offset:2048
	s_nop 0
	v_addc_co_u32_e32 v127, vcc, 0, v127, vcc
	global_load_dwordx4 v[152:155], v[152:153], off
	s_add_i32 s8, s8, 4
	global_load_dwordx4 v[180:183], v[126:127], off offset:2048
	s_addk_i32 s0, 0x80
	v_add_u32_e32 v208, 16, v208
	v_lshl_add_u64 v[114:115], v[114:115], 0, s[22:23]
	s_cmp_lt_i32 s8, 62
	s_waitcnt vmcnt(6)
	v_mfma_f32_16x16x32_bf16 v[188:191], v[132:135], v[8:11], 0
	s_waitcnt vmcnt(4) lgkmcnt(3)
	v_lshrrev_b32_e32 v204, v98, v156
	v_mfma_f32_16x16x32_bf16 v[184:187], v[140:143], v[8:11], 0
	s_waitcnt lgkmcnt(2)
	v_lshrrev_b32_e32 v203, v97, v157
	v_and_b32_e32 v156, 1, v203
	v_and_b32_e32 v157, 1, v204
	v_mfma_f32_16x16x32_bf16 v[188:191], v[122:125], v[16:19], v[188:191]
	v_cmp_ne_u32_e32 vcc, 0, v156
	v_and_b32_e32 v156, 2, v203
	s_waitcnt lgkmcnt(1)
; #define MFMA16(a, b, c) __builtin_amdgcn_mfma_f32_16x16x32_bf16((a), (b), (c), 0, 0, 0)
; DI void attn_block(const Params& p, int isP, int sq, int c, int h) {
;     ...
;       for (int qt = 0; qt < 4; ++qt) {
;         if (qt < nqt) {
;           f32x4 sa = {0.f, 0.f, 0.f, 0.f}, sb = {0.f, 0.f, 0.f, 0.f};
;           sa = MFMA16(ka0, qf[qt][0], sa); sa = MFMA16(ka1, qf[qt][1], sa);
;           sb = MFMA16(kb0, qf[qt][0], sb); sb = MFMA16(kb1, qf[qt][1], sb);
;           const unsigned mb = (mw[qt] >> (fq * 8)) & 0xFFu;
;           float pr[8];
; #pragma unroll
;           for (int i = 0; i < 4; ++i) {
;             float pa_ = __builtin_amdgcn_exp2f(sa[i] * sc2 - mref[qt]);
;             float pb_ = __builtin_amdgcn_exp2f(sb[i] * sc2 - mref[qt]);
;             pr[i] = ((mb >> i) & 1u) ? pa_ : 0.f;
;             pr[4 + i] = ((mb >> (4 + i)) & 1u) ? pb_ : 0.f;
;           }
;           lsum[qt] += ((pr[0] + pr[1]) + (pr[2] + pr[3])) + ((pr[4] + pr[5]) + (pr[6] + pr[7]));
;           union { unsigned u[4]; bf16x8 v; } pk;
;           pk.u[0] = pack2(pr[0], pr[1]); pk.u[1] = pack2(pr[2], pr[3]); pk.u[2] = pack2(pr[4], pr[5]); pk.u[3] = pack2(pr[6], pr[7]);
; #pragma unroll
;           for (int dt = 0; dt < 4; ++dt) o[qt][dt] = MFMA16(vf[dt], pk.v, o[qt][dt]);
	v_lshrrev_b32_e32 v159, v98, v159
	v_mfma_f32_16x16x32_bf16 v[184:187], v[136:139], v[16:19], v[184:187]
	s_nop 2
	v_fma_f32 v127, v188, s33, -v118
	v_exp_f32_e32 v192, v127
	s_nop 2
	v_fma_f32 v127, v185, s33, -v118
	v_exp_f32_e32 v193, v127
	v_fma_f32 v127, v189, s33, -v118
	v_exp_f32_e32 v194, v127
	v_fma_f32 v127, v186, s33, -v118
	v_exp_f32_e32 v195, v127
	v_fma_f32 v127, v190, s33, -v118
	v_fma_f32 v126, v184, s33, -v118
	v_exp_f32_e32 v196, v127
	v_fma_f32 v127, v187, s33, -v118
	v_mfma_f32_16x16x32_bf16 v[184:187], v[140:143], v[28:31], 0
	v_exp_f32_e32 v197, v127
	v_fma_f32 v127, v191, s33, -v118
	v_exp_f32_e32 v198, v127
	v_mfma_f32_16x16x32_bf16 v[188:191], v[132:135], v[28:31], 0
	v_exp_f32_e32 v126, v126
	v_mfma_f32_16x16x32_bf16 v[184:187], v[136:139], v[32:35], v[184:187]
	v_mfma_f32_16x16x32_bf16 v[188:191], v[122:125], v[32:35], v[188:191]
	s_nop 6
	v_fma_f32 v127, v184, s33, -v119
	v_exp_f32_e32 v127, v127
	v_fma_f32 v185, v185, s33, -v119
	v_fma_f32 v184, v188, s33, -v119
	v_exp_f32_e32 v185, v185
	v_fma_f32 v188, v189, s33, -v119
	v_exp_f32_e32 v199, v188
	v_fma_f32 v186, v186, s33, -v119
	v_fma_f32 v188, v190, s33, -v119
	v_exp_f32_e32 v186, v186
	v_exp_f32_e32 v200, v188
	v_fma_f32 v188, v191, s33, -v119
	v_cndmask_b32_e32 v127, 0, v127, vcc
	v_cmp_ne_u32_e32 vcc, 0, v157
	v_fma_f32 v187, v187, s33, -v119
	v_exp_f32_e32 v201, v188
	v_cndmask_b32_e32 v126, 0, v126, vcc
	v_and_b32_e32 v188, 2, v204
	v_cmp_ne_u32_e32 vcc, 0, v156
	v_exp_f32_e32 v187, v187
	v_exp_f32_e32 v184, v184
	v_cndmask_b32_e32 v157, 0, v185, vcc
	v_cmp_ne_u32_e32 vcc, 0, v188
	v_and_b32_e32 v185, 4, v203
	v_and_b32_e32 v188, 4, v204
	v_cndmask_b32_e32 v156, 0, v193, vcc
	v_cmp_ne_u32_e32 vcc, 0, v185
	v_and_b32_e32 v185, 8, v203
	s_nop 0
	v_cndmask_b32_e32 v189, 0, v186, vcc
	v_cmp_ne_u32_e32 vcc, 0, v188
	v_and_b32_e32 v186, 8, v204
	s_nop 0
	v_cndmask_b32_e32 v188, 0, v195, vcc
	v_cmp_ne_u32_e32 vcc, 0, v185
	v_and_b32_e32 v185, 16, v203
	s_nop 0
	v_cndmask_b32_e32 v191, 0, v187, vcc
	v_cmp_ne_u32_e32 vcc, 0, v186
	v_and_b32_e32 v186, 16, v204
	s_nop 0
	v_cndmask_b32_e32 v190, 0, v197, vcc
	v_cmp_ne_u32_e32 vcc, 0, v185
	v_and_b32_e32 v185, 32, v204
	s_nop 0
	v_cndmask_b32_e32 v193, 0, v184, vcc
	v_cmp_ne_u32_e32 vcc, 0, v186
	v_and_b32_e32 v184, 32, v203
	v_pk_add_f32 v[186:187], v[188:189], v[190:191]
	v_cndmask_b32_e32 v192, 0, v192, vcc
	v_cmp_ne_u32_e32 vcc, 0, v184
	v_and_b32_e32 v184, 64, v203
	s_nop 0
	v_cndmask_b32_e32 v195, 0, v199, vcc
	v_cmp_ne_u32_e32 vcc, 0, v185
	v_and_b32_e32 v185, 64, v204
	s_nop 0
	v_cndmask_b32_e32 v194, 0, v194, vcc
	v_cmp_ne_u32_e32 vcc, 0, v184
	v_and_b32_e32 v184, 0x80, v203
	s_nop 0
	v_cndmask_b32_e32 v197, 0, v200, vcc
	v_cmp_ne_u32_e32 vcc, 0, v185
	v_and_b32_e32 v185, 0x80, v204
	s_nop 0
	v_cndmask_b32_e32 v196, 0, v196, vcc
	v_cmp_ne_u32_e32 vcc, 0, v184
	s_nop 1
	v_cndmask_b32_e32 v199, 0, v201, vcc
	v_cmp_ne_u32_e32 vcc, 0, v185
	v_pk_add_f32 v[184:185], v[126:127], v[156:157]
	s_nop 0
	v_cndmask_b32_e32 v198, 0, v198, vcc
	v_pk_add_f32 v[184:185], v[184:185], v[186:187]
	v_pk_add_f32 v[186:187], v[192:193], v[194:195]
	v_pk_add_f32 v[200:201], v[196:197], v[198:199]
	s_nop 0
	v_pk_add_f32 v[186:187], v[186:187], v[200:201]
	s_nop 0
	v_pk_add_f32 v[200:201], v[184:185], v[186:187]
	v_cvt_pk_bf16_f32 v184, v126, v156
	v_cvt_pk_bf16_f32 v185, v188, v190
	v_cvt_pk_bf16_f32 v186, v192, v194
	v_cvt_pk_bf16_f32 v187, v196, v198
	v_pk_add_f32 v[104:105], v[104:105], v[200:201]
	s_waitcnt vmcnt(3)
	v_mfma_f32_16x16x32_bf16 v[64:67], v[144:147], v[184:187], v[64:67]
	s_waitcnt vmcnt(2)
	v_mfma_f32_16x16x32_bf16 v[92:95], v[148:151], v[184:187], v[92:95]
	s_waitcnt vmcnt(1)
	v_mfma_f32_16x16x32_bf16 v[88:91], v[152:155], v[184:187], v[88:91]
	s_waitcnt vmcnt(0) lgkmcnt(0)
; #define MFMA16(a, b, c) __builtin_amdgcn_mfma_f32_16x16x32_bf16((a), (b), (c), 0, 0, 0)
; DI void attn_block(const Params& p, int isP, int sq, int c, int h) {
;     ...
;       for (int qt = 0; qt < 4; ++qt) {
;         if (qt < nqt) {
;           f32x4 sa = {0.f, 0.f, 0.f, 0.f}, sb = {0.f, 0.f, 0.f, 0.f};
;           sa = MFMA16(ka0, qf[qt][0], sa); sa = MFMA16(ka1, qf[qt][1], sa);
;           sb = MFMA16(kb0, qf[qt][0], sb); sb = MFMA16(kb1, qf[qt][1], sb);
;           const unsigned mb = (mw[qt] >> (fq * 8)) & 0xFFu;
;           float pr[8];
; #pragma unroll
;           for (int i = 0; i < 4; ++i) {
;             float pa_ = __builtin_amdgcn_exp2f(sa[i] * sc2 - mref[qt]);
;             float pb_ = __builtin_amdgcn_exp2f(sb[i] * sc2 - mref[qt]);
;             pr[i] = ((mb >> i) & 1u) ? pa_ : 0.f;
;             pr[4 + i] = ((mb >> (4 + i)) & 1u) ? pb_ : 0.f;
;           }
;           lsum[qt] += ((pr[0] + pr[1]) + (pr[2] + pr[3])) + ((pr[4] + pr[5]) + (pr[6] + pr[7]));
;           union { unsigned u[4]; bf16x8 v; } pk;
;           pk.u[0] = pack2(pr[0], pr[1]); pk.u[1] = pack2(pr[2], pr[3]); pk.u[2] = pack2(pr[4], pr[5]); pk.u[3] = pack2(pr[6], pr[7]);
; #pragma unroll
;           for (int dt = 0; dt < 4; ++dt) o[qt][dt] = MFMA16(vf[dt], pk.v, o[qt][dt]);
;         }
;       }
;       ka0 = nka0; ka1 = nka1; kb0 = nkb0; kb1 = nkb1;
; #pragma unroll
;       for (int dt = 0; dt < 4; ++dt) vf[dt] = nvf[dt];
; #pragma unroll
;       for (int qt = 0; qt < 4; ++qt) mw[qt] = nmw[qt];
;     }
	v_mfma_f32_16x16x32_bf16 v[84:87], v[180:183], v[184:187], v[84:87]
	v_cvt_pk_bf16_f32 v184, v127, v157
	v_cvt_pk_bf16_f32 v185, v189, v191
	v_cvt_pk_bf16_f32 v186, v193, v195
	v_cvt_pk_bf16_f32 v187, v197, v199
	v_mfma_f32_16x16x32_bf16 v[188:191], v[132:135], v[48:51], 0
	s_nop 0
	v_mfma_f32_16x16x32_bf16 v[80:83], v[144:147], v[184:187], v[80:83]
	v_mfma_f32_16x16x32_bf16 v[76:79], v[148:151], v[184:187], v[76:79]
	v_mfma_f32_16x16x32_bf16 v[72:75], v[152:155], v[184:187], v[72:75]
	v_mfma_f32_16x16x32_bf16 v[68:71], v[180:183], v[184:187], v[68:71]
	v_mfma_f32_16x16x32_bf16 v[184:187], v[140:143], v[48:51], 0
	v_mfma_f32_16x16x32_bf16 v[188:191], v[122:125], v[52:55], v[188:191]
	v_mfma_f32_16x16x32_bf16 v[184:187], v[136:139], v[52:55], v[184:187]
	v_mfma_f32_16x16x32_bf16 v[140:143], v[140:143], v[56:59], 0
	s_nop 5
	v_fma_f32 v127, v188, s33, -v120
	v_exp_f32_e32 v156, v127
	v_fma_f32 v127, v185, s33, -v120
	v_exp_f32_e32 v157, v127
	v_fma_f32 v127, v189, s33, -v120
	v_fma_f32 v126, v184, s33, -v120
	v_exp_f32_e32 v184, v127
	v_fma_f32 v127, v186, s33, -v120
	v_mfma_f32_16x16x32_bf16 v[136:139], v[136:139], v[60:63], v[140:143]
	v_exp_f32_e32 v185, v127
	v_fma_f32 v127, v190, s33, -v120
	v_exp_f32_e32 v186, v127
	v_mfma_f32_16x16x32_bf16 v[132:135], v[132:135], v[56:59], 0
	v_fma_f32 v127, v187, s33, -v120
	v_exp_f32_e32 v187, v127
	v_fma_f32 v127, v191, s33, -v120
	v_exp_f32_e32 v188, v127
	v_fma_f32 v127, v136, s33, -v121
	v_mfma_f32_16x16x32_bf16 v[122:125], v[122:125], v[60:63], v[132:135]
	v_exp_f32_e32 v127, v127
	v_exp_f32_e32 v126, v126
	v_lshrrev_b32_e32 v189, v97, v202
	v_fma_f32 v133, v138, s33, -v121
	v_fma_f32 v132, v137, s33, -v121
	v_exp_f32_e32 v134, v133
	v_fma_f32 v133, v139, s33, -v121
	v_exp_f32_e32 v132, v132
	v_exp_f32_e32 v136, v133
	v_and_b32_e32 v133, 1, v189
	v_and_b32_e32 v135, 1, v159
	v_cmp_ne_u32_e32 vcc, 0, v133
	v_and_b32_e32 v133, 2, v189
	v_fma_f32 v122, v122, s33, -v121
	v_cndmask_b32_e32 v127, 0, v127, vcc
	v_cmp_ne_u32_e32 vcc, 0, v135
	v_and_b32_e32 v135, 2, v159
	v_and_b32_e32 v137, 4, v159
	v_cndmask_b32_e32 v126, 0, v126, vcc
	v_cmp_ne_u32_e32 vcc, 0, v133
	v_exp_f32_e32 v122, v122
	v_fma_f32 v123, v123, s33, -v121
	v_cndmask_b32_e32 v133, 0, v132, vcc
	v_cmp_ne_u32_e32 vcc, 0, v135
	v_and_b32_e32 v135, 4, v189
	v_and_b32_e32 v138, 8, v159
	v_cndmask_b32_e32 v132, 0, v157, vcc
	v_cmp_ne_u32_e32 vcc, 0, v135
	v_exp_f32_e32 v123, v123
	v_fma_f32 v124, v124, s33, -v121
	v_cndmask_b32_e32 v135, 0, v134, vcc
	v_cmp_ne_u32_e32 vcc, 0, v137
	v_and_b32_e32 v137, 8, v189
	v_and_b32_e32 v140, 16, v159
	v_cndmask_b32_e32 v134, 0, v185, vcc
	v_cmp_ne_u32_e32 vcc, 0, v137
	v_exp_f32_e32 v124, v124
	v_fma_f32 v125, v125, s33, -v121
	v_cndmask_b32_e32 v137, 0, v136, vcc
	v_cmp_ne_u32_e32 vcc, 0, v138
	v_and_b32_e32 v138, 16, v189
	v_exp_f32_e32 v125, v125
	v_cndmask_b32_e32 v136, 0, v187, vcc
	v_cmp_ne_u32_e32 vcc, 0, v138
	s_nop 1
	v_cndmask_b32_e32 v139, 0, v122, vcc
	v_cmp_ne_u32_e32 vcc, 0, v140
	v_and_b32_e32 v122, 32, v189
	v_and_b32_e32 v140, 32, v159
	v_cndmask_b32_e32 v138, 0, v156, vcc
	v_cmp_ne_u32_e32 vcc, 0, v122
	v_and_b32_e32 v122, 64, v189
	s_nop 0
	v_cndmask_b32_e32 v141, 0, v123, vcc
	v_cmp_ne_u32_e32 vcc, 0, v140
	v_and_b32_e32 v123, 64, v159
	s_nop 0
	v_cndmask_b32_e32 v140, 0, v184, vcc
	v_cmp_ne_u32_e32 vcc, 0, v122
	v_and_b32_e32 v122, 0x80, v189
	s_nop 0
	v_cndmask_b32_e32 v143, 0, v124, vcc
	v_cmp_ne_u32_e32 vcc, 0, v123
	v_and_b32_e32 v123, 0x80, v159
	s_nop 0
	v_cndmask_b32_e32 v142, 0, v186, vcc
	v_cmp_ne_u32_e32 vcc, 0, v122
	s_nop 1
	v_cndmask_b32_e32 v157, 0, v125, vcc
	v_cmp_ne_u32_e32 vcc, 0, v123
	v_pk_add_f32 v[122:123], v[126:127], v[132:133]
	v_pk_add_f32 v[124:125], v[134:135], v[136:137]
	v_cndmask_b32_e32 v156, 0, v188, vcc
	v_pk_add_f32 v[122:123], v[122:123], v[124:125]
	v_pk_add_f32 v[124:125], v[138:139], v[140:141]
	v_pk_add_f32 v[184:185], v[142:143], v[156:157]
	s_nop 0
	v_pk_add_f32 v[124:125], v[124:125], v[184:185]
	s_nop 0
	v_pk_add_f32 v[184:185], v[122:123], v[124:125]
	v_cvt_pk_bf16_f32 v122, v126, v132
	v_cvt_pk_bf16_f32 v123, v134, v136
	v_cvt_pk_bf16_f32 v124, v138, v140
	v_cvt_pk_bf16_f32 v125, v142, v156
	v_pk_add_f32 v[100:101], v[100:101], v[184:185]
	s_nop 0
	v_mfma_f32_16x16x32_bf16 v[44:47], v[144:147], v[122:125], v[44:47]
	v_mfma_f32_16x16x32_bf16 v[40:43], v[148:151], v[122:125], v[40:43]
	v_mfma_f32_16x16x32_bf16 v[36:39], v[152:155], v[122:125], v[36:39]
	v_mfma_f32_16x16x32_bf16 v[24:27], v[180:183], v[122:125], v[24:27]
	v_cvt_pk_bf16_f32 v122, v127, v133
	v_cvt_pk_bf16_f32 v123, v135, v137
	v_cvt_pk_bf16_f32 v124, v139, v141
	v_cvt_pk_bf16_f32 v125, v143, v157
	s_nop 1
	v_mfma_f32_16x16x32_bf16 v[20:23], v[144:147], v[122:125], v[20:23]
	v_mfma_f32_16x16x32_bf16 v[12:15], v[148:151], v[122:125], v[12:15]
	v_mfma_f32_16x16x32_bf16 v[4:7], v[152:155], v[122:125], v[4:7]
	v_mfma_f32_16x16x32_bf16 v[0:3], v[180:183], v[122:125], v[0:3]
	s_cbranch_scc1 .LBB0_4853
